# kv_b and out-proj epilogues: rsq loads hoisted + counted vmcnt; sc1 write-through on dwordx4 epilogue stores of gate-up, down, out-proj, kv_b
# baseline (speedup 1.0000x reference)
; __device__ __forceinline__ u32x4 pack8(f32x4 v0, f32x4 v1) { u32x4 w; w.x = cvt_pk_bf16(v0[0], v0[1]); w.y = cvt_pk_bf16(v0[2], v0[3]); w.z = cvt_pk_bf16(v1[0], v1[1]); w.w = cvt_pk_bf16(v1[2], v1[3]); return w; }
;     __device__ __forceinline__ void operator()(EPI_ARGS) const {
; #pragma unroll
;         for (int ai = 0; ai < 2; ++ai)
; #pragma unroll
;             for (int m = 0; m < 4; ++m) { const int row = EPI_ROW(ai, m); const float rstd = rsq ? __builtin_amdgcn_rsqf(rsq[row] * inv_n + RMS_EPS) : 1.f;
; #pragma unroll
;                 for (int bj = 0; bj < 2; ++bj) *(u32x4*)(O + (size_t)row * ld + EPI_COL(bj)) = pack8(acc[ai][bj][m][0] * rstd, acc[ai][bj][m][1] * rstd);
;                 asm volatile("" ::: "memory"); }
;     }
.LBB0_357:
	v_lshl_add_u32 v136, s94, 8, v140
	v_ashrrev_i32_e32 v137, 31, v136
	v_lshl_add_u64 v[150:151], v[136:137], 2, s[30:31]
	global_load_dword v216, v[150:151], off
	global_load_dword v217, v[150:151], off offset:64
	global_load_dword v218, v[150:151], off offset:128
	global_load_dword v219, v[150:151], off offset:192
	global_load_dword v220, v[150:151], off offset:512
	global_load_dword v221, v[150:151], off offset:576
	global_load_dword v222, v[150:151], off offset:640
	global_load_dword v223, v[150:151], off offset:704
	v_lshl_or_b32 v148, s93, 8, v141
	v_ashrrev_i32_e32 v149, 31, v148
	s_andn2_b64 vcc, exec, s[4:5]
	s_waitcnt vmcnt(7)
	v_fmamk_f32 v137, v216, 0x3b800000, v147
	v_rsq_f32_e32 v150, v137
	s_nop 0
	v_pk_mul_f32 v[126:127], v[126:127], v[150:151] op_sel_hi:[1,0]
	v_pk_mul_f32 v[124:125], v[124:125], v[150:151] op_sel_hi:[1,0]
	v_pk_mul_f32 v[120:121], v[120:121], v[150:151] op_sel_hi:[1,0]
	v_pk_mul_f32 v[122:123], v[122:123], v[150:151] op_sel_hi:[1,0]
	v_cvt_pk_bf16_f32 v124, v124, v125
	v_cvt_pk_bf16_f32 v125, v126, v127
	v_cvt_pk_bf16_f32 v126, v120, v121
	v_mov_b64_e32 v[120:121], s[86:87]
	v_cvt_pk_bf16_f32 v127, v122, v123
	v_mad_i64_i32 v[152:153], s[8:9], v136, s84, v[120:121]
	v_lshlrev_b64 v[122:123], 1, v[148:149]
	v_lshl_add_u64 v[148:149], v[152:153], 0, v[122:123]
	global_store_dwordx4 v[148:149], v[124:127], off sc1
	v_pk_mul_f32 v[116:117], v[116:117], v[150:151] op_sel_hi:[1,0]
	v_pk_mul_f32 v[118:119], v[118:119], v[150:151] op_sel_hi:[1,0]
	v_pk_mul_f32 v[124:125], v[114:115], v[150:151] op_sel_hi:[1,0]
	v_pk_mul_f32 v[114:115], v[112:113], v[150:151] op_sel_hi:[1,0]
	v_cvt_pk_bf16_f32 v112, v116, v117
	v_cvt_pk_bf16_f32 v113, v118, v119
	s_nop 0
	v_cvt_pk_bf16_f32 v114, v114, v115
	v_cvt_pk_bf16_f32 v115, v124, v125
	global_store_dwordx4 v[148:149], v[112:115], off offset:256 sc1
	s_nop 1
	v_or_b32_e32 v112, 16, v136
	v_ashrrev_i32_e32 v113, 31, v112
	v_lshl_add_u64 v[114:115], v[112:113], 2, s[30:31]
	s_nop 1
	s_waitcnt vmcnt(8)
	v_fmamk_f32 v113, v217, 0x3b800000, v147
	v_rsq_f32_e32 v114, v113
	s_nop 0
	v_pk_mul_f32 v[108:109], v[108:109], v[114:115] op_sel_hi:[1,0]
	v_pk_mul_f32 v[116:117], v[106:107], v[114:115] op_sel_hi:[1,0]
	v_pk_mul_f32 v[106:107], v[104:105], v[114:115] op_sel_hi:[1,0]
	v_cvt_pk_bf16_f32 v104, v108, v109
	v_mad_i64_i32 v[108:109], s[8:9], v112, s84, v[120:121]
	v_pk_mul_f32 v[110:111], v[110:111], v[114:115] op_sel_hi:[1,0]
	v_lshl_add_u64 v[108:109], v[108:109], 0, v[122:123]
	v_cvt_pk_bf16_f32 v105, v110, v111
	v_cvt_pk_bf16_f32 v106, v106, v107
	v_cvt_pk_bf16_f32 v107, v116, v117
	global_store_dwordx4 v[108:109], v[104:107], off sc1
	v_pk_mul_f32 v[100:101], v[100:101], v[114:115] op_sel_hi:[1,0]
	v_pk_mul_f32 v[102:103], v[102:103], v[114:115] op_sel_hi:[1,0]
	v_pk_mul_f32 v[104:105], v[98:99], v[114:115] op_sel_hi:[1,0]
	v_pk_mul_f32 v[98:99], v[96:97], v[114:115] op_sel_hi:[1,0]
	v_cvt_pk_bf16_f32 v96, v100, v101
	v_cvt_pk_bf16_f32 v97, v102, v103
	s_nop 0
	v_cvt_pk_bf16_f32 v98, v98, v99
	v_cvt_pk_bf16_f32 v99, v104, v105
	global_store_dwordx4 v[108:109], v[96:99], off offset:256 sc1
	s_nop 1
	v_or_b32_e32 v96, 32, v136
	v_ashrrev_i32_e32 v97, 31, v96
	v_lshl_add_u64 v[98:99], v[96:97], 2, s[30:31]
	s_nop 1
	s_waitcnt vmcnt(9)
	v_fmamk_f32 v97, v218, 0x3b800000, v147
	v_rsq_f32_e32 v98, v97
	s_nop 0
	v_pk_mul_f32 v[92:93], v[92:93], v[98:99] op_sel_hi:[1,0]
	v_pk_mul_f32 v[100:101], v[90:91], v[98:99] op_sel_hi:[1,0]
	v_pk_mul_f32 v[90:91], v[88:89], v[98:99] op_sel_hi:[1,0]
	v_cvt_pk_bf16_f32 v88, v92, v93
	v_mad_i64_i32 v[92:93], s[8:9], v96, s84, v[120:121]
	v_pk_mul_f32 v[94:95], v[94:95], v[98:99] op_sel_hi:[1,0]
	v_lshl_add_u64 v[92:93], v[92:93], 0, v[122:123]
	v_cvt_pk_bf16_f32 v89, v94, v95
	v_cvt_pk_bf16_f32 v90, v90, v91
	v_cvt_pk_bf16_f32 v91, v100, v101
	global_store_dwordx4 v[92:93], v[88:91], off sc1
	v_pk_mul_f32 v[84:85], v[84:85], v[98:99] op_sel_hi:[1,0]
	v_pk_mul_f32 v[86:87], v[86:87], v[98:99] op_sel_hi:[1,0]
	v_pk_mul_f32 v[88:89], v[82:83], v[98:99] op_sel_hi:[1,0]
	v_pk_mul_f32 v[82:83], v[80:81], v[98:99] op_sel_hi:[1,0]
	v_cvt_pk_bf16_f32 v80, v84, v85
	v_cvt_pk_bf16_f32 v81, v86, v87
	s_nop 0
	v_cvt_pk_bf16_f32 v82, v82, v83
	v_cvt_pk_bf16_f32 v83, v88, v89
	global_store_dwordx4 v[92:93], v[80:83], off offset:256 sc1
	s_nop 1
	v_or_b32_e32 v80, 48, v136
	v_ashrrev_i32_e32 v81, 31, v80
	v_lshl_add_u64 v[82:83], v[80:81], 2, s[30:31]
	s_nop 1
	s_waitcnt vmcnt(10)
	v_fmamk_f32 v81, v219, 0x3b800000, v147
	v_rsq_f32_e32 v82, v81
	s_nop 0
	v_pk_mul_f32 v[76:77], v[76:77], v[82:83] op_sel_hi:[1,0]
	v_pk_mul_f32 v[84:85], v[74:75], v[82:83] op_sel_hi:[1,0]
	v_pk_mul_f32 v[74:75], v[72:73], v[82:83] op_sel_hi:[1,0]
	v_cvt_pk_bf16_f32 v72, v76, v77
	v_mad_i64_i32 v[76:77], s[8:9], v80, s84, v[120:121]
	v_pk_mul_f32 v[78:79], v[78:79], v[82:83] op_sel_hi:[1,0]
	v_lshl_add_u64 v[76:77], v[76:77], 0, v[122:123]
	v_cvt_pk_bf16_f32 v73, v78, v79
	v_cvt_pk_bf16_f32 v74, v74, v75
	v_cvt_pk_bf16_f32 v75, v84, v85
	global_store_dwordx4 v[76:77], v[72:75], off sc1
	v_pk_mul_f32 v[68:69], v[68:69], v[82:83] op_sel_hi:[1,0]
	v_pk_mul_f32 v[70:71], v[70:71], v[82:83] op_sel_hi:[1,0]
	v_pk_mul_f32 v[72:73], v[66:67], v[82:83] op_sel_hi:[1,0]
	v_pk_mul_f32 v[66:67], v[64:65], v[82:83] op_sel_hi:[1,0]
	v_cvt_pk_bf16_f32 v64, v68, v69
	v_cvt_pk_bf16_f32 v65, v70, v71
	s_nop 0
	v_cvt_pk_bf16_f32 v66, v66, v67
	v_cvt_pk_bf16_f32 v67, v72, v73
	global_store_dwordx4 v[76:77], v[64:67], off offset:256 sc1
	s_nop 1
	v_add_u32_e32 v64, 0x80, v136
	v_ashrrev_i32_e32 v65, 31, v64
	v_lshl_add_u64 v[66:67], v[64:65], 2, s[30:31]
	s_nop 1
	s_waitcnt vmcnt(11)
; __device__ __forceinline__ u32x4 pack8(f32x4 v0, f32x4 v1) { u32x4 w; w.x = cvt_pk_bf16(v0[0], v0[1]); w.y = cvt_pk_bf16(v0[2], v0[3]); w.z = cvt_pk_bf16(v1[0], v1[1]); w.w = cvt_pk_bf16(v1[2], v1[3]); return w; }
;     __device__ __forceinline__ void operator()(EPI_ARGS) const {
; #pragma unroll
;         for (int ai = 0; ai < 2; ++ai)
; #pragma unroll
;             for (int m = 0; m < 4; ++m) { const int row = EPI_ROW(ai, m); const float rstd = rsq ? __builtin_amdgcn_rsqf(rsq[row] * inv_n + RMS_EPS) : 1.f;
; #pragma unroll
;                 for (int bj = 0; bj < 2; ++bj) *(u32x4*)(O + (size_t)row * ld + EPI_COL(bj)) = pack8(acc[ai][bj][m][0] * rstd, acc[ai][bj][m][1] * rstd);
;                 asm volatile("" ::: "memory"); }
;     }
	v_fmamk_f32 v65, v220, 0x3b800000, v147
	v_rsq_f32_e32 v66, v65
	s_nop 0
	v_pk_mul_f32 v[60:61], v[60:61], v[66:67] op_sel_hi:[1,0]
	v_pk_mul_f32 v[68:69], v[58:59], v[66:67] op_sel_hi:[1,0]
	v_pk_mul_f32 v[58:59], v[56:57], v[66:67] op_sel_hi:[1,0]
	v_cvt_pk_bf16_f32 v56, v60, v61
	v_mad_i64_i32 v[60:61], s[8:9], v64, s84, v[120:121]
	v_pk_mul_f32 v[62:63], v[62:63], v[66:67] op_sel_hi:[1,0]
	v_lshl_add_u64 v[60:61], v[60:61], 0, v[122:123]
	v_cvt_pk_bf16_f32 v57, v62, v63
	v_cvt_pk_bf16_f32 v58, v58, v59
	v_cvt_pk_bf16_f32 v59, v68, v69
	global_store_dwordx4 v[60:61], v[56:59], off sc1
	v_pk_mul_f32 v[52:53], v[52:53], v[66:67] op_sel_hi:[1,0]
	v_pk_mul_f32 v[54:55], v[54:55], v[66:67] op_sel_hi:[1,0]
	v_pk_mul_f32 v[56:57], v[50:51], v[66:67] op_sel_hi:[1,0]
	v_pk_mul_f32 v[50:51], v[48:49], v[66:67] op_sel_hi:[1,0]
	v_cvt_pk_bf16_f32 v48, v52, v53
	v_cvt_pk_bf16_f32 v49, v54, v55
	s_nop 0
	v_cvt_pk_bf16_f32 v50, v50, v51
	v_cvt_pk_bf16_f32 v51, v56, v57
	global_store_dwordx4 v[60:61], v[48:51], off offset:256 sc1
	s_nop 1
	v_add_u32_e32 v48, 0x90, v136
	v_ashrrev_i32_e32 v49, 31, v48
	v_lshl_add_u64 v[50:51], v[48:49], 2, s[30:31]
	s_nop 1
	s_waitcnt vmcnt(12)
	v_fmamk_f32 v49, v221, 0x3b800000, v147
	v_rsq_f32_e32 v50, v49
	s_nop 0
	v_pk_mul_f32 v[44:45], v[44:45], v[50:51] op_sel_hi:[1,0]
	v_pk_mul_f32 v[52:53], v[42:43], v[50:51] op_sel_hi:[1,0]
	v_pk_mul_f32 v[42:43], v[40:41], v[50:51] op_sel_hi:[1,0]
	v_cvt_pk_bf16_f32 v40, v44, v45
	v_mad_i64_i32 v[44:45], s[8:9], v48, s84, v[120:121]
	v_pk_mul_f32 v[46:47], v[46:47], v[50:51] op_sel_hi:[1,0]
	v_lshl_add_u64 v[44:45], v[44:45], 0, v[122:123]
	v_cvt_pk_bf16_f32 v41, v46, v47
	v_cvt_pk_bf16_f32 v42, v42, v43
	v_cvt_pk_bf16_f32 v43, v52, v53
	global_store_dwordx4 v[44:45], v[40:43], off sc1
	v_pk_mul_f32 v[36:37], v[36:37], v[50:51] op_sel_hi:[1,0]
	v_pk_mul_f32 v[38:39], v[38:39], v[50:51] op_sel_hi:[1,0]
	v_pk_mul_f32 v[40:41], v[34:35], v[50:51] op_sel_hi:[1,0]
	v_pk_mul_f32 v[34:35], v[32:33], v[50:51] op_sel_hi:[1,0]
	v_cvt_pk_bf16_f32 v32, v36, v37
	v_cvt_pk_bf16_f32 v33, v38, v39
	s_nop 0
	v_cvt_pk_bf16_f32 v34, v34, v35
	v_cvt_pk_bf16_f32 v35, v40, v41
	global_store_dwordx4 v[44:45], v[32:35], off offset:256 sc1
	s_nop 1
	v_add_u32_e32 v32, 0xa0, v136
	v_ashrrev_i32_e32 v33, 31, v32
	v_lshl_add_u64 v[34:35], v[32:33], 2, s[30:31]
	s_nop 1
	s_waitcnt vmcnt(13)
	v_fmamk_f32 v33, v222, 0x3b800000, v147
	v_rsq_f32_e32 v34, v33
	s_nop 0
	v_pk_mul_f32 v[28:29], v[28:29], v[34:35] op_sel_hi:[1,0]
	v_pk_mul_f32 v[36:37], v[26:27], v[34:35] op_sel_hi:[1,0]
	v_pk_mul_f32 v[26:27], v[24:25], v[34:35] op_sel_hi:[1,0]
	v_cvt_pk_bf16_f32 v24, v28, v29
	v_mad_i64_i32 v[28:29], s[8:9], v32, s84, v[120:121]
	v_pk_mul_f32 v[30:31], v[30:31], v[34:35] op_sel_hi:[1,0]
	v_lshl_add_u64 v[28:29], v[28:29], 0, v[122:123]
	v_cvt_pk_bf16_f32 v25, v30, v31
	v_cvt_pk_bf16_f32 v26, v26, v27
	v_cvt_pk_bf16_f32 v27, v36, v37
	global_store_dwordx4 v[28:29], v[24:27], off sc1
	v_pk_mul_f32 v[20:21], v[20:21], v[34:35] op_sel_hi:[1,0]
	v_pk_mul_f32 v[22:23], v[22:23], v[34:35] op_sel_hi:[1,0]
	v_pk_mul_f32 v[24:25], v[18:19], v[34:35] op_sel_hi:[1,0]
	v_pk_mul_f32 v[18:19], v[16:17], v[34:35] op_sel_hi:[1,0]
	v_cvt_pk_bf16_f32 v16, v20, v21
	v_cvt_pk_bf16_f32 v17, v22, v23
	s_nop 0
	v_cvt_pk_bf16_f32 v18, v18, v19
	v_cvt_pk_bf16_f32 v19, v24, v25
	global_store_dwordx4 v[28:29], v[16:19], off offset:256 sc1
	s_nop 1
	v_add_u32_e32 v16, 0xb0, v136
	v_ashrrev_i32_e32 v17, 31, v16
	v_lshl_add_u64 v[18:19], v[16:17], 2, s[30:31]
	s_nop 1
	s_waitcnt vmcnt(14)
	v_fmamk_f32 v17, v223, 0x3b800000, v147
	v_rsq_f32_e32 v18, v17
	s_nop 0
	v_pk_mul_f32 v[12:13], v[12:13], v[18:19] op_sel_hi:[1,0]
	v_pk_mul_f32 v[20:21], v[10:11], v[18:19] op_sel_hi:[1,0]
	v_pk_mul_f32 v[10:11], v[8:9], v[18:19] op_sel_hi:[1,0]
	v_cvt_pk_bf16_f32 v8, v12, v13
	v_mad_i64_i32 v[12:13], s[8:9], v16, s84, v[120:121]
	v_pk_mul_f32 v[14:15], v[14:15], v[18:19] op_sel_hi:[1,0]
	v_lshl_add_u64 v[12:13], v[12:13], 0, v[122:123]
	v_cvt_pk_bf16_f32 v9, v14, v15
	v_cvt_pk_bf16_f32 v10, v10, v11
	v_cvt_pk_bf16_f32 v11, v20, v21
	global_store_dwordx4 v[12:13], v[8:11], off sc1
	v_pk_mul_f32 v[6:7], v[6:7], v[18:19] op_sel_hi:[1,0]
	v_pk_mul_f32 v[4:5], v[4:5], v[18:19] op_sel_hi:[1,0]
	v_pk_mul_f32 v[8:9], v[2:3], v[18:19] op_sel_hi:[1,0]
	v_pk_mul_f32 v[2:3], v[0:1], v[18:19] op_sel_hi:[1,0]
	v_cvt_pk_bf16_f32 v0, v4, v5
	v_cvt_pk_bf16_f32 v1, v6, v7
	s_mov_b64 s[8:9], -1
	v_cvt_pk_bf16_f32 v2, v2, v3
	v_cvt_pk_bf16_f32 v3, v8, v9
	global_store_dwordx4 v[12:13], v[0:3], off offset:256 sc1
	s_cbranch_vccnz .LBB0_350
	s_andn2_b64 vcc, exec, s[0:1]
	s_cbranch_vccnz .LBB0_349
	s_barrier
	s_branch .LBB0_349

; __device__ __forceinline__ u32x4 pack8(f32x4 v0, f32x4 v1) { u32x4 w; w.x = cvt_pk_bf16(v0[0], v0[1]); w.y = cvt_pk_bf16(v0[2], v0[3]); w.z = cvt_pk_bf16(v1[0], v1[1]); w.w = cvt_pk_bf16(v1[2], v1[3]); return w; }
;     __device__ __forceinline__ void operator()(EPI_ARGS) const {
; #pragma unroll
;         for (int ai = 0; ai < 2; ++ai)
; #pragma unroll
;             for (int m = 0; m < 4; ++m) { const int row = EPI_ROW(ai, m); const float rs = __builtin_amdgcn_rsqf(rsqs[row] * (1.f / 1024.f) + RMS_EPS);
; #pragma unroll
;                 for (int bj = 0; bj < 2; ++bj) *(u32x4*)(O + (size_t)row * 2048 + EPI_COL(bj)) = pack8(acc[ai][bj][m][0] * rs, acc[ai][bj][m][1] * rs);
;                 asm volatile("" ::: "memory"); }
;     }
.LBB0_774:
	v_ashrrev_i32_e32 v137, 31, v136
	v_lshl_add_u64 v[2:3], v[136:137], 2, s[64:65]
	global_load_dword v216, v[2:3], off
	global_load_dword v217, v[2:3], off offset:64
	global_load_dword v218, v[2:3], off offset:128
	global_load_dword v219, v[2:3], off offset:192
	global_load_dword v220, v[2:3], off offset:512
	global_load_dword v221, v[2:3], off offset:576
	global_load_dword v222, v[2:3], off offset:640
	global_load_dword v223, v[2:3], off offset:704
	v_lshl_or_b32 v2, s53, 8, v151
	v_lshlrev_b64 v[156:157], 12, v[136:137]
	v_ashrrev_i32_e32 v3, 31, v2
	v_lshl_add_u64 v[156:157], s[86:87], 0, v[156:157]
	v_lshlrev_b64 v[2:3], 1, v[2:3]
	v_or_b32_e32 v138, 16, v136
	v_lshl_add_u64 v[156:157], v[156:157], 0, v[2:3]
	v_ashrrev_i32_e32 v139, 31, v138
	v_lshl_add_u64 v[166:167], v[138:139], 2, s[64:65]
	s_andn2_b64 vcc, exec, s[0:1]
	s_mov_b64 s[0:1], -1
	s_waitcnt vmcnt(7)
	v_fmamk_f32 v1, v216, 0x3a800000, v152
	v_rsq_f32_e32 v158, v1
	s_nop 0
	v_pk_mul_f32 v[130:131], v[130:131], v[158:159] op_sel_hi:[1,0]
	v_pk_mul_f32 v[128:129], v[128:129], v[158:159] op_sel_hi:[1,0]
	v_pk_mul_f32 v[126:127], v[126:127], v[158:159] op_sel_hi:[1,0]
	v_pk_mul_f32 v[124:125], v[124:125], v[158:159] op_sel_hi:[1,0]
	v_pk_mul_f32 v[122:123], v[122:123], v[158:159] op_sel_hi:[1,0]
	v_pk_mul_f32 v[120:121], v[120:121], v[158:159] op_sel_hi:[1,0]
	v_pk_mul_f32 v[172:173], v[118:119], v[158:159] op_sel_hi:[1,0]
	v_pk_mul_f32 v[158:159], v[116:117], v[158:159] op_sel_hi:[1,0]
	v_cvt_pk_bf16_f32 v116, v128, v129
	v_cvt_pk_bf16_f32 v117, v130, v131
	v_cvt_pk_bf16_f32 v118, v124, v125
	v_cvt_pk_bf16_f32 v119, v126, v127
	global_store_dwordx4 v[156:157], v[116:119], off sc1
	s_nop 1
	v_cvt_pk_bf16_f32 v116, v120, v121
	v_cvt_pk_bf16_f32 v117, v122, v123
	v_cvt_pk_bf16_f32 v118, v158, v159
	v_cvt_pk_bf16_f32 v119, v172, v173
	global_store_dwordx4 v[156:157], v[116:119], off offset:256 sc1
	s_nop 1
	s_waitcnt vmcnt(8)
	v_fmamk_f32 v1, v217, 0x3a800000, v152
	v_rsq_f32_e32 v120, v1
	v_lshlrev_b64 v[118:119], 12, v[138:139]
	v_lshl_add_u64 v[118:119], s[86:87], 0, v[118:119]
	v_or_b32_e32 v116, 32, v136
	v_lshl_add_u64 v[118:119], v[118:119], 0, v[2:3]
	v_pk_mul_f32 v[114:115], v[114:115], v[120:121] op_sel_hi:[1,0]
	v_pk_mul_f32 v[112:113], v[112:113], v[120:121] op_sel_hi:[1,0]
	v_pk_mul_f32 v[110:111], v[110:111], v[120:121] op_sel_hi:[1,0]
	v_pk_mul_f32 v[108:109], v[108:109], v[120:121] op_sel_hi:[1,0]
	v_pk_mul_f32 v[106:107], v[106:107], v[120:121] op_sel_hi:[1,0]
	v_pk_mul_f32 v[104:105], v[104:105], v[120:121] op_sel_hi:[1,0]
	v_pk_mul_f32 v[124:125], v[102:103], v[120:121] op_sel_hi:[1,0]
	v_pk_mul_f32 v[120:121], v[100:101], v[120:121] op_sel_hi:[1,0]
	v_cvt_pk_bf16_f32 v100, v112, v113
	v_cvt_pk_bf16_f32 v101, v114, v115
	v_cvt_pk_bf16_f32 v102, v108, v109
	v_cvt_pk_bf16_f32 v103, v110, v111
	v_ashrrev_i32_e32 v117, 31, v116
	global_store_dwordx4 v[118:119], v[100:103], off sc1
	v_lshl_add_u64 v[122:123], v[116:117], 2, s[64:65]
	s_nop 0
	v_cvt_pk_bf16_f32 v100, v104, v105
	v_cvt_pk_bf16_f32 v101, v106, v107
	v_cvt_pk_bf16_f32 v102, v120, v121
	v_cvt_pk_bf16_f32 v103, v124, v125
	global_store_dwordx4 v[118:119], v[100:103], off offset:256 sc1
	s_nop 1
	s_waitcnt vmcnt(9)
	v_fmamk_f32 v1, v218, 0x3a800000, v152
	v_rsq_f32_e32 v104, v1
	v_lshlrev_b64 v[102:103], 12, v[116:117]
	v_lshl_add_u64 v[102:103], s[86:87], 0, v[102:103]
	v_or_b32_e32 v100, 48, v136
	v_lshl_add_u64 v[102:103], v[102:103], 0, v[2:3]
	v_pk_mul_f32 v[98:99], v[98:99], v[104:105] op_sel_hi:[1,0]
	v_pk_mul_f32 v[96:97], v[96:97], v[104:105] op_sel_hi:[1,0]
	v_pk_mul_f32 v[94:95], v[94:95], v[104:105] op_sel_hi:[1,0]
	v_pk_mul_f32 v[92:93], v[92:93], v[104:105] op_sel_hi:[1,0]
	v_pk_mul_f32 v[90:91], v[90:91], v[104:105] op_sel_hi:[1,0]
	v_pk_mul_f32 v[88:89], v[88:89], v[104:105] op_sel_hi:[1,0]
	v_pk_mul_f32 v[108:109], v[86:87], v[104:105] op_sel_hi:[1,0]
	v_pk_mul_f32 v[104:105], v[84:85], v[104:105] op_sel_hi:[1,0]
	v_cvt_pk_bf16_f32 v84, v96, v97
	v_cvt_pk_bf16_f32 v85, v98, v99
	v_cvt_pk_bf16_f32 v86, v92, v93
	v_cvt_pk_bf16_f32 v87, v94, v95
	v_ashrrev_i32_e32 v101, 31, v100
	global_store_dwordx4 v[102:103], v[84:87], off sc1
	v_lshl_add_u64 v[106:107], v[100:101], 2, s[64:65]
	s_nop 0
	v_cvt_pk_bf16_f32 v84, v88, v89
	v_cvt_pk_bf16_f32 v85, v90, v91
	v_cvt_pk_bf16_f32 v86, v104, v105
	v_cvt_pk_bf16_f32 v87, v108, v109
	global_store_dwordx4 v[102:103], v[84:87], off offset:256 sc1
	s_nop 1
	s_waitcnt vmcnt(10)
	v_fmamk_f32 v1, v219, 0x3a800000, v152
	v_rsq_f32_e32 v88, v1
	v_lshlrev_b64 v[86:87], 12, v[100:101]
	v_lshl_add_u64 v[86:87], s[86:87], 0, v[86:87]
	v_add_u32_e32 v84, 0x80, v136
	v_lshl_add_u64 v[86:87], v[86:87], 0, v[2:3]
	v_pk_mul_f32 v[82:83], v[82:83], v[88:89] op_sel_hi:[1,0]
	v_pk_mul_f32 v[80:81], v[80:81], v[88:89] op_sel_hi:[1,0]
	v_pk_mul_f32 v[78:79], v[78:79], v[88:89] op_sel_hi:[1,0]
	v_pk_mul_f32 v[76:77], v[76:77], v[88:89] op_sel_hi:[1,0]
	v_pk_mul_f32 v[74:75], v[74:75], v[88:89] op_sel_hi:[1,0]
	v_pk_mul_f32 v[72:73], v[72:73], v[88:89] op_sel_hi:[1,0]
	v_pk_mul_f32 v[92:93], v[70:71], v[88:89] op_sel_hi:[1,0]
	v_pk_mul_f32 v[88:89], v[68:69], v[88:89] op_sel_hi:[1,0]
	v_cvt_pk_bf16_f32 v68, v80, v81
	v_cvt_pk_bf16_f32 v69, v82, v83
	v_cvt_pk_bf16_f32 v70, v76, v77
	v_cvt_pk_bf16_f32 v71, v78, v79
	v_ashrrev_i32_e32 v85, 31, v84
	global_store_dwordx4 v[86:87], v[68:71], off sc1
	v_lshl_add_u64 v[90:91], v[84:85], 2, s[64:65]
	s_nop 0
	v_cvt_pk_bf16_f32 v68, v72, v73
	v_cvt_pk_bf16_f32 v69, v74, v75
	v_cvt_pk_bf16_f32 v70, v88, v89
	v_cvt_pk_bf16_f32 v71, v92, v93
	global_store_dwordx4 v[86:87], v[68:71], off offset:256 sc1
	s_nop 1
	s_waitcnt vmcnt(11)
; __device__ __forceinline__ u32x4 pack8(f32x4 v0, f32x4 v1) { u32x4 w; w.x = cvt_pk_bf16(v0[0], v0[1]); w.y = cvt_pk_bf16(v0[2], v0[3]); w.z = cvt_pk_bf16(v1[0], v1[1]); w.w = cvt_pk_bf16(v1[2], v1[3]); return w; }
;     __device__ __forceinline__ void operator()(EPI_ARGS) const {
; #pragma unroll
;         for (int ai = 0; ai < 2; ++ai)
; #pragma unroll
;             for (int m = 0; m < 4; ++m) { const int row = EPI_ROW(ai, m); const float rs = __builtin_amdgcn_rsqf(rsqs[row] * (1.f / 1024.f) + RMS_EPS);
; #pragma unroll
;                 for (int bj = 0; bj < 2; ++bj) *(u32x4*)(O + (size_t)row * 2048 + EPI_COL(bj)) = pack8(acc[ai][bj][m][0] * rs, acc[ai][bj][m][1] * rs);
;                 asm volatile("" ::: "memory"); }
;     }
	v_fmamk_f32 v1, v220, 0x3a800000, v152
	v_rsq_f32_e32 v72, v1
	v_lshlrev_b64 v[70:71], 12, v[84:85]
	v_lshl_add_u64 v[70:71], s[86:87], 0, v[70:71]
	v_add_u32_e32 v68, 0x90, v136
	v_lshl_add_u64 v[70:71], v[70:71], 0, v[2:3]
	v_pk_mul_f32 v[66:67], v[66:67], v[72:73] op_sel_hi:[1,0]
	v_pk_mul_f32 v[64:65], v[64:65], v[72:73] op_sel_hi:[1,0]
	v_pk_mul_f32 v[62:63], v[62:63], v[72:73] op_sel_hi:[1,0]
	v_pk_mul_f32 v[60:61], v[60:61], v[72:73] op_sel_hi:[1,0]
	v_pk_mul_f32 v[58:59], v[58:59], v[72:73] op_sel_hi:[1,0]
	v_pk_mul_f32 v[56:57], v[56:57], v[72:73] op_sel_hi:[1,0]
	v_pk_mul_f32 v[76:77], v[54:55], v[72:73] op_sel_hi:[1,0]
	v_pk_mul_f32 v[72:73], v[52:53], v[72:73] op_sel_hi:[1,0]
	v_cvt_pk_bf16_f32 v52, v64, v65
	v_cvt_pk_bf16_f32 v53, v66, v67
	v_cvt_pk_bf16_f32 v54, v60, v61
	v_cvt_pk_bf16_f32 v55, v62, v63
	v_ashrrev_i32_e32 v69, 31, v68
	global_store_dwordx4 v[70:71], v[52:55], off sc1
	v_lshl_add_u64 v[74:75], v[68:69], 2, s[64:65]
	s_nop 0
	v_cvt_pk_bf16_f32 v52, v56, v57
	v_cvt_pk_bf16_f32 v53, v58, v59
	v_cvt_pk_bf16_f32 v54, v72, v73
	v_cvt_pk_bf16_f32 v55, v76, v77
	global_store_dwordx4 v[70:71], v[52:55], off offset:256 sc1
	s_nop 1
	s_waitcnt vmcnt(12)
	v_fmamk_f32 v1, v221, 0x3a800000, v152
	v_rsq_f32_e32 v56, v1
	v_lshlrev_b64 v[54:55], 12, v[68:69]
	v_lshl_add_u64 v[54:55], s[86:87], 0, v[54:55]
	v_add_u32_e32 v52, 0xa0, v136
	v_lshl_add_u64 v[54:55], v[54:55], 0, v[2:3]
	v_pk_mul_f32 v[50:51], v[50:51], v[56:57] op_sel_hi:[1,0]
	v_pk_mul_f32 v[48:49], v[48:49], v[56:57] op_sel_hi:[1,0]
	v_pk_mul_f32 v[46:47], v[46:47], v[56:57] op_sel_hi:[1,0]
	v_pk_mul_f32 v[44:45], v[44:45], v[56:57] op_sel_hi:[1,0]
	v_pk_mul_f32 v[42:43], v[42:43], v[56:57] op_sel_hi:[1,0]
	v_pk_mul_f32 v[40:41], v[40:41], v[56:57] op_sel_hi:[1,0]
	v_pk_mul_f32 v[60:61], v[38:39], v[56:57] op_sel_hi:[1,0]
	v_pk_mul_f32 v[56:57], v[36:37], v[56:57] op_sel_hi:[1,0]
	v_cvt_pk_bf16_f32 v36, v48, v49
	v_cvt_pk_bf16_f32 v37, v50, v51
	v_cvt_pk_bf16_f32 v38, v44, v45
	v_cvt_pk_bf16_f32 v39, v46, v47
	v_ashrrev_i32_e32 v53, 31, v52
	global_store_dwordx4 v[54:55], v[36:39], off sc1
	v_lshl_add_u64 v[58:59], v[52:53], 2, s[64:65]
	s_nop 0
	v_cvt_pk_bf16_f32 v36, v40, v41
	v_cvt_pk_bf16_f32 v37, v42, v43
	v_cvt_pk_bf16_f32 v38, v56, v57
	v_cvt_pk_bf16_f32 v39, v60, v61
	global_store_dwordx4 v[54:55], v[36:39], off offset:256 sc1
	s_nop 1
	s_waitcnt vmcnt(13)
	v_fmamk_f32 v1, v222, 0x3a800000, v152
	v_rsq_f32_e32 v40, v1
	v_lshlrev_b64 v[38:39], 12, v[52:53]
	v_lshl_add_u64 v[38:39], s[86:87], 0, v[38:39]
	v_add_u32_e32 v36, 0xb0, v136
	v_lshl_add_u64 v[38:39], v[38:39], 0, v[2:3]
	v_pk_mul_f32 v[34:35], v[34:35], v[40:41] op_sel_hi:[1,0]
	v_pk_mul_f32 v[32:33], v[32:33], v[40:41] op_sel_hi:[1,0]
	v_pk_mul_f32 v[30:31], v[30:31], v[40:41] op_sel_hi:[1,0]
	v_pk_mul_f32 v[28:29], v[28:29], v[40:41] op_sel_hi:[1,0]
	v_pk_mul_f32 v[26:27], v[26:27], v[40:41] op_sel_hi:[1,0]
	v_pk_mul_f32 v[24:25], v[24:25], v[40:41] op_sel_hi:[1,0]
	v_pk_mul_f32 v[44:45], v[22:23], v[40:41] op_sel_hi:[1,0]
	v_pk_mul_f32 v[40:41], v[20:21], v[40:41] op_sel_hi:[1,0]
	v_cvt_pk_bf16_f32 v20, v32, v33
	v_cvt_pk_bf16_f32 v21, v34, v35
	v_cvt_pk_bf16_f32 v22, v28, v29
	v_cvt_pk_bf16_f32 v23, v30, v31
	v_ashrrev_i32_e32 v37, 31, v36
	global_store_dwordx4 v[38:39], v[20:23], off sc1
	v_lshl_add_u64 v[42:43], v[36:37], 2, s[64:65]
	s_nop 0
	v_cvt_pk_bf16_f32 v20, v24, v25
	v_cvt_pk_bf16_f32 v21, v26, v27
	v_cvt_pk_bf16_f32 v22, v40, v41
	v_cvt_pk_bf16_f32 v23, v44, v45
	global_store_dwordx4 v[38:39], v[20:23], off offset:256 sc1
	s_nop 1
	s_waitcnt vmcnt(14)
	v_fmamk_f32 v1, v223, 0x3a800000, v152
	v_rsq_f32_e32 v20, v1
	v_lshlrev_b64 v[22:23], 12, v[36:37]
	v_lshl_add_u64 v[22:23], s[86:87], 0, v[22:23]
	v_lshl_add_u64 v[22:23], v[22:23], 0, v[2:3]
	v_pk_mul_f32 v[2:3], v[16:17], v[20:21] op_sel_hi:[1,0]
	v_pk_mul_f32 v[18:19], v[18:19], v[20:21] op_sel_hi:[1,0]
	v_pk_mul_f32 v[14:15], v[14:15], v[20:21] op_sel_hi:[1,0]
	v_pk_mul_f32 v[12:13], v[12:13], v[20:21] op_sel_hi:[1,0]
	v_pk_mul_f32 v[16:17], v[4:5], v[20:21] op_sel_hi:[1,0]
	v_cvt_pk_bf16_f32 v2, v2, v3
	v_cvt_pk_bf16_f32 v3, v18, v19
	v_cvt_pk_bf16_f32 v4, v12, v13
	v_cvt_pk_bf16_f32 v5, v14, v15
	v_pk_mul_f32 v[10:11], v[10:11], v[20:21] op_sel_hi:[1,0]
	v_pk_mul_f32 v[8:9], v[8:9], v[20:21] op_sel_hi:[1,0]
	v_pk_mul_f32 v[6:7], v[6:7], v[20:21] op_sel_hi:[1,0]
	global_store_dwordx4 v[22:23], v[2:5], off sc1
	s_nop 1
	v_cvt_pk_bf16_f32 v2, v8, v9
	v_cvt_pk_bf16_f32 v3, v10, v11
	v_cvt_pk_bf16_f32 v4, v16, v17
	v_cvt_pk_bf16_f32 v5, v6, v7
	global_store_dwordx4 v[22:23], v[2:5], off offset:256 sc1
	s_cbranch_vccnz .LBB0_765
	s_andn2_b64 vcc, exec, s[8:9]
	s_cbranch_vccnz .LBB0_764
	s_barrier
	s_branch .LBB0_764

; __device__ __forceinline__ u32x4 pack8(f32x4 v0, f32x4 v1) { u32x4 w; w.x = cvt_pk_bf16(v0[0], v0[1]); w.y = cvt_pk_bf16(v0[2], v0[3]); w.z = cvt_pk_bf16(v1[0], v1[1]); w.w = cvt_pk_bf16(v1[2], v1[3]); return w; }
;     __device__ __forceinline__ void operator()(EPI_ARGS) const {
;         const int col0 = u.pn * 128 + wc * 32 + 8 * fq;
; #pragma unroll
;         for (int ai = 0; ai < 2; ++ai)
; #pragma unroll
;             for (int m = 0; m < 4; ++m) { const int row = EPI_ROW(ai, m); const float rs = __builtin_amdgcn_rsqf(rsq[row] * (1.f / DM) + RMS_EPS); f32x4 v0, v1;
;                 const float c1 = -1.4426950408889634f * rs, rs2 = rs * rs;
;                 { const f32x4 g = acc[ai][0][m][0], u = acc[ai][1][m][0]; f32x4 t = g * c1, r;
; #pragma unroll
;                   for (int e = 0; e < 4; ++e) t[e] = __builtin_amdgcn_exp2f(t[e]);
;                   t = t + 1.f;
; #pragma unroll
;                   for (int e = 0; e < 4; ++e) r[e] = __builtin_amdgcn_rcpf(t[e]);
;                   v0 = (g * u) * (r * rs2); }
;                 { const f32x4 g = acc[ai][0][m][1], u = acc[ai][1][m][1]; f32x4 t = g * c1, r;
; #pragma unroll
;                   for (int e = 0; e < 4; ++e) t[e] = __builtin_amdgcn_exp2f(t[e]);
;                   t = t + 1.f;
; #pragma unroll
;                   for (int e = 0; e < 4; ++e) r[e] = __builtin_amdgcn_rcpf(t[e]);
;                   v1 = (g * u) * (r * rs2); }
;                 *(u32x4*)(H + (size_t)row * DFF + col0) = pack8(v0, v1);
;                 if (m & 1) asm volatile("" ::: "memory"); }
.LBB0_899:
	v_lshl_add_u32 v132, s50, 8, v139
	v_ashrrev_i32_e32 v133, 31, v132
	v_lshl_add_u64 v[154:155], v[132:133], 2, s[8:9]
	global_load_dword v224, v[154:155], off
	global_load_dword v225, v[154:155], off offset:64
	global_load_dword v226, v[154:155], off offset:128
	global_load_dword v227, v[154:155], off offset:192
	global_load_dword v228, v[154:155], off offset:512
	global_load_dword v229, v[154:155], off offset:576
	global_load_dword v230, v[154:155], off offset:640
	global_load_dword v231, v[154:155], off offset:704
	v_pk_mul_f32 v[126:127], v[118:119], v[126:127]
	v_pk_mul_f32 v[124:125], v[116:117], v[124:125]
	v_pk_mul_f32 v[156:157], v[114:115], v[122:123]
	v_pk_mul_f32 v[158:159], v[112:113], v[120:121]
	v_lshl_or_b32 v154, s49, 7, v146
	v_mov_b64_e32 v[120:121], s[64:65]
	v_ashrrev_i32_e32 v155, 31, v154
	v_mad_i64_i32 v[166:167], s[26:27], v132, s46, v[120:121]
	v_or_b32_e32 v172, 16, v132
	v_lshlrev_b64 v[122:123], 1, v[154:155]
	v_ashrrev_i32_e32 v173, 31, v172
	v_lshl_add_u64 v[154:155], v[166:167], 0, v[122:123]
	v_lshl_add_u64 v[166:167], v[172:173], 2, s[8:9]
	v_pk_mul_f32 v[110:111], v[102:103], v[110:111]
	v_pk_mul_f32 v[108:109], v[100:101], v[108:109]
	v_pk_mul_f32 v[106:107], v[98:99], v[106:107]
	v_pk_mul_f32 v[104:105], v[96:97], v[104:105]
	v_pk_mul_f32 v[94:95], v[86:87], v[94:95]
	v_pk_mul_f32 v[92:93], v[84:85], v[92:93]
	v_pk_mul_f32 v[90:91], v[82:83], v[90:91]
	v_pk_mul_f32 v[88:89], v[80:81], v[88:89]
	v_pk_mul_f32 v[78:79], v[70:71], v[78:79]
	v_pk_mul_f32 v[76:77], v[68:69], v[76:77]
	v_pk_mul_f32 v[74:75], v[66:67], v[74:75]
	v_pk_mul_f32 v[72:73], v[64:65], v[72:73]
	v_pk_mul_f32 v[62:63], v[54:55], v[62:63]
	v_pk_mul_f32 v[60:61], v[52:53], v[60:61]
	v_pk_mul_f32 v[58:59], v[50:51], v[58:59]
	v_pk_mul_f32 v[56:57], v[48:49], v[56:57]
	v_pk_mul_f32 v[46:47], v[38:39], v[46:47]
	v_pk_mul_f32 v[44:45], v[36:37], v[44:45]
	v_pk_mul_f32 v[42:43], v[34:35], v[42:43]
	v_pk_mul_f32 v[40:41], v[32:33], v[40:41]
	v_pk_mul_f32 v[30:31], v[22:23], v[30:31]
	v_pk_mul_f32 v[28:29], v[20:21], v[28:29]
	v_pk_mul_f32 v[26:27], v[18:19], v[26:27]
	v_pk_mul_f32 v[24:25], v[16:17], v[24:25]
	v_pk_mul_f32 v[14:15], v[10:11], v[14:15]
	v_pk_mul_f32 v[12:13], v[8:9], v[12:13]
	v_pk_mul_f32 v[2:3], v[6:7], v[2:3]
	v_pk_mul_f32 v[0:1], v[4:5], v[0:1]
	s_andn2_b64 vcc, exec, s[4:5]
	s_mov_b64 s[4:5], -1
	s_waitcnt vmcnt(7)
	v_fmamk_f32 v133, v224, 0x3a000000, v152
	v_rsq_f32_e32 v133, v133
	s_nop 0
	v_mul_f32_e32 v174, 0xbfb8aa3b, v133
	v_pk_mul_f32 v[118:119], v[118:119], v[174:175] op_sel_hi:[1,0]
	v_pk_mul_f32 v[116:117], v[116:117], v[174:175] op_sel_hi:[1,0]
	v_pk_mul_f32 v[114:115], v[114:115], v[174:175] op_sel_hi:[1,0]
	v_pk_mul_f32 v[112:113], v[112:113], v[174:175] op_sel_hi:[1,0]
	v_exp_f32_e32 v116, v116
	v_exp_f32_e32 v117, v117
	v_exp_f32_e32 v118, v118
	v_exp_f32_e32 v119, v119
	v_exp_f32_e32 v112, v112
	v_exp_f32_e32 v113, v113
	v_exp_f32_e32 v114, v114
	v_exp_f32_e32 v115, v115
	v_add_f32_e32 v116, 1.0, v116
	v_add_f32_e32 v117, 1.0, v117
	v_add_f32_e32 v118, 1.0, v118
	v_add_f32_e32 v119, 1.0, v119
	v_mul_f32_e32 v176, v133, v133
	v_add_f32_e32 v133, 1.0, v112
	v_add_f32_e32 v153, 1.0, v113
	v_add_f32_e32 v161, 1.0, v114
	v_add_f32_e32 v163, 1.0, v115
	v_rcp_f32_e32 v112, v116
	v_rcp_f32_e32 v113, v117
	v_rcp_f32_e32 v114, v118
	v_rcp_f32_e32 v115, v119
	v_rcp_f32_e32 v116, v133
	v_rcp_f32_e32 v117, v153
	v_rcp_f32_e32 v118, v161
	v_rcp_f32_e32 v119, v163
	v_pk_mul_f32 v[112:113], v[176:177], v[112:113] op_sel_hi:[0,1]
	v_pk_mul_f32 v[114:115], v[176:177], v[114:115] op_sel_hi:[0,1]
	v_pk_mul_f32 v[116:117], v[176:177], v[116:117] op_sel_hi:[0,1]
	v_pk_mul_f32 v[118:119], v[176:177], v[118:119] op_sel_hi:[0,1]
	v_pk_mul_f32 v[114:115], v[126:127], v[114:115]
	v_pk_mul_f32 v[112:113], v[124:125], v[112:113]
	v_pk_mul_f32 v[118:119], v[156:157], v[118:119]
	v_pk_mul_f32 v[116:117], v[158:159], v[116:117]
	v_cvt_pk_bf16_f32 v112, v112, v113
	v_cvt_pk_bf16_f32 v113, v114, v115
	s_nop 0
	v_cvt_pk_bf16_f32 v114, v116, v117
	v_cvt_pk_bf16_f32 v115, v118, v119
	global_store_dwordx4 v[154:155], v[112:115], off sc1
	s_nop 1
	s_nop 0
	v_or_b32_e32 v112, 32, v132
	v_mad_i64_i32 v[114:115], s[26:27], v172, s46, v[120:121]
	v_lshl_add_u64 v[114:115], v[114:115], 0, v[122:123]
	s_waitcnt vmcnt(7)
	v_fmamk_f32 v113, v225, 0x3a000000, v152
	v_rsq_f32_e32 v119, v113
	v_ashrrev_i32_e32 v113, 31, v112
	v_lshl_add_u64 v[116:117], v[112:113], 2, s[8:9]
	v_mul_f32_e32 v118, 0xbfb8aa3b, v119
	v_pk_mul_f32 v[102:103], v[102:103], v[118:119] op_sel_hi:[1,0]
	v_pk_mul_f32 v[100:101], v[100:101], v[118:119] op_sel_hi:[1,0]
	v_pk_mul_f32 v[98:99], v[98:99], v[118:119] op_sel_hi:[1,0]
	v_pk_mul_f32 v[96:97], v[96:97], v[118:119] op_sel_hi:[1,0]
	v_exp_f32_e32 v100, v100
	v_exp_f32_e32 v101, v101
	v_exp_f32_e32 v102, v102
	v_exp_f32_e32 v103, v103
	v_exp_f32_e32 v96, v96
	v_exp_f32_e32 v97, v97
	v_exp_f32_e32 v98, v98
	v_exp_f32_e32 v99, v99
	v_add_f32_e32 v100, 1.0, v100
	v_add_f32_e32 v101, 1.0, v101
	v_add_f32_e32 v102, 1.0, v102
	v_add_f32_e32 v103, 1.0, v103
	v_mul_f32_e32 v124, v119, v119
	v_add_f32_e32 v113, 1.0, v96
	v_add_f32_e32 v118, 1.0, v97
	v_add_f32_e32 v119, 1.0, v98
	v_add_f32_e32 v125, 1.0, v99
	v_rcp_f32_e32 v96, v100
	v_rcp_f32_e32 v97, v101
	v_rcp_f32_e32 v98, v102
	v_rcp_f32_e32 v99, v103
	v_rcp_f32_e32 v100, v113
	v_rcp_f32_e32 v101, v118
	v_rcp_f32_e32 v102, v119
	v_rcp_f32_e32 v103, v125
	v_pk_mul_f32 v[96:97], v[124:125], v[96:97] op_sel_hi:[0,1]
	v_pk_mul_f32 v[98:99], v[124:125], v[98:99] op_sel_hi:[0,1]
	v_pk_mul_f32 v[100:101], v[124:125], v[100:101] op_sel_hi:[0,1]
	v_pk_mul_f32 v[102:103], v[124:125], v[102:103] op_sel_hi:[0,1]
	v_pk_mul_f32 v[98:99], v[110:111], v[98:99]
	v_pk_mul_f32 v[96:97], v[108:109], v[96:97]
	v_pk_mul_f32 v[102:103], v[106:107], v[102:103]
	v_pk_mul_f32 v[100:101], v[104:105], v[100:101]
	v_cvt_pk_bf16_f32 v96, v96, v97
	v_cvt_pk_bf16_f32 v97, v98, v99
	s_nop 0
	v_cvt_pk_bf16_f32 v98, v100, v101
	v_cvt_pk_bf16_f32 v99, v102, v103
	global_store_dwordx4 v[114:115], v[96:99], off sc1
	s_nop 1
	s_nop 0
	v_or_b32_e32 v96, 48, v132
	v_mad_i64_i32 v[98:99], s[26:27], v112, s46, v[120:121]
	v_lshl_add_u64 v[98:99], v[98:99], 0, v[122:123]
	s_waitcnt vmcnt(7)
; __device__ __forceinline__ u32x4 pack8(f32x4 v0, f32x4 v1) { u32x4 w; w.x = cvt_pk_bf16(v0[0], v0[1]); w.y = cvt_pk_bf16(v0[2], v0[3]); w.z = cvt_pk_bf16(v1[0], v1[1]); w.w = cvt_pk_bf16(v1[2], v1[3]); return w; }
;     __device__ __forceinline__ void operator()(EPI_ARGS) const {
;         const int col0 = u.pn * 128 + wc * 32 + 8 * fq;
; #pragma unroll
;         for (int ai = 0; ai < 2; ++ai)
; #pragma unroll
;             for (int m = 0; m < 4; ++m) { const int row = EPI_ROW(ai, m); const float rs = __builtin_amdgcn_rsqf(rsq[row] * (1.f / DM) + RMS_EPS); f32x4 v0, v1;
;                 const float c1 = -1.4426950408889634f * rs, rs2 = rs * rs;
;                 { const f32x4 g = acc[ai][0][m][0], u = acc[ai][1][m][0]; f32x4 t = g * c1, r;
; #pragma unroll
;                   for (int e = 0; e < 4; ++e) t[e] = __builtin_amdgcn_exp2f(t[e]);
;                   t = t + 1.f;
; #pragma unroll
;                   for (int e = 0; e < 4; ++e) r[e] = __builtin_amdgcn_rcpf(t[e]);
;                   v0 = (g * u) * (r * rs2); }
;                 { const f32x4 g = acc[ai][0][m][1], u = acc[ai][1][m][1]; f32x4 t = g * c1, r;
; #pragma unroll
;                   for (int e = 0; e < 4; ++e) t[e] = __builtin_amdgcn_exp2f(t[e]);
;                   t = t + 1.f;
; #pragma unroll
;                   for (int e = 0; e < 4; ++e) r[e] = __builtin_amdgcn_rcpf(t[e]);
;                   v1 = (g * u) * (r * rs2); }
;                 *(u32x4*)(H + (size_t)row * DFF + col0) = pack8(v0, v1);
;                 if (m & 1) asm volatile("" ::: "memory"); }
	v_fmamk_f32 v97, v226, 0x3a000000, v152
	v_rsq_f32_e32 v103, v97
	v_ashrrev_i32_e32 v97, 31, v96
	v_lshl_add_u64 v[100:101], v[96:97], 2, s[8:9]
	v_mul_f32_e32 v102, 0xbfb8aa3b, v103
	v_pk_mul_f32 v[86:87], v[86:87], v[102:103] op_sel_hi:[1,0]
	v_pk_mul_f32 v[84:85], v[84:85], v[102:103] op_sel_hi:[1,0]
	v_pk_mul_f32 v[82:83], v[82:83], v[102:103] op_sel_hi:[1,0]
	v_pk_mul_f32 v[80:81], v[80:81], v[102:103] op_sel_hi:[1,0]
	v_exp_f32_e32 v84, v84
	v_exp_f32_e32 v85, v85
	v_exp_f32_e32 v86, v86
	v_exp_f32_e32 v87, v87
	v_exp_f32_e32 v80, v80
	v_exp_f32_e32 v81, v81
	v_exp_f32_e32 v82, v82
	v_exp_f32_e32 v83, v83
	v_add_f32_e32 v84, 1.0, v84
	v_add_f32_e32 v85, 1.0, v85
	v_add_f32_e32 v86, 1.0, v86
	v_add_f32_e32 v87, 1.0, v87
	v_mul_f32_e32 v104, v103, v103
	v_add_f32_e32 v97, 1.0, v80
	v_add_f32_e32 v102, 1.0, v81
	v_add_f32_e32 v103, 1.0, v82
	v_add_f32_e32 v105, 1.0, v83
	v_rcp_f32_e32 v80, v84
	v_rcp_f32_e32 v81, v85
	v_rcp_f32_e32 v82, v86
	v_rcp_f32_e32 v83, v87
	v_rcp_f32_e32 v84, v97
	v_rcp_f32_e32 v85, v102
	v_rcp_f32_e32 v86, v103
	v_rcp_f32_e32 v87, v105
	v_pk_mul_f32 v[80:81], v[104:105], v[80:81] op_sel_hi:[0,1]
	v_pk_mul_f32 v[82:83], v[104:105], v[82:83] op_sel_hi:[0,1]
	v_pk_mul_f32 v[84:85], v[104:105], v[84:85] op_sel_hi:[0,1]
	v_pk_mul_f32 v[86:87], v[104:105], v[86:87] op_sel_hi:[0,1]
	v_pk_mul_f32 v[82:83], v[94:95], v[82:83]
	v_pk_mul_f32 v[80:81], v[92:93], v[80:81]
	v_pk_mul_f32 v[86:87], v[90:91], v[86:87]
	v_pk_mul_f32 v[84:85], v[88:89], v[84:85]
	v_cvt_pk_bf16_f32 v80, v80, v81
	v_cvt_pk_bf16_f32 v81, v82, v83
	s_nop 0
	v_cvt_pk_bf16_f32 v82, v84, v85
	v_cvt_pk_bf16_f32 v83, v86, v87
	global_store_dwordx4 v[98:99], v[80:83], off sc1
	s_nop 1
	s_nop 0
	v_add_u32_e32 v80, 0x80, v132
	v_mad_i64_i32 v[82:83], s[26:27], v96, s46, v[120:121]
	v_lshl_add_u64 v[82:83], v[82:83], 0, v[122:123]
	s_waitcnt vmcnt(7)
	v_fmamk_f32 v81, v227, 0x3a000000, v152
	v_rsq_f32_e32 v87, v81
	v_ashrrev_i32_e32 v81, 31, v80
	v_lshl_add_u64 v[84:85], v[80:81], 2, s[8:9]
	v_mul_f32_e32 v86, 0xbfb8aa3b, v87
	v_pk_mul_f32 v[70:71], v[70:71], v[86:87] op_sel_hi:[1,0]
	v_pk_mul_f32 v[68:69], v[68:69], v[86:87] op_sel_hi:[1,0]
	v_pk_mul_f32 v[66:67], v[66:67], v[86:87] op_sel_hi:[1,0]
	v_pk_mul_f32 v[64:65], v[64:65], v[86:87] op_sel_hi:[1,0]
	v_exp_f32_e32 v68, v68
	v_exp_f32_e32 v69, v69
	v_exp_f32_e32 v70, v70
	v_exp_f32_e32 v71, v71
	v_exp_f32_e32 v64, v64
	v_exp_f32_e32 v65, v65
	v_exp_f32_e32 v66, v66
	v_exp_f32_e32 v67, v67
	v_add_f32_e32 v68, 1.0, v68
	v_add_f32_e32 v69, 1.0, v69
	v_add_f32_e32 v70, 1.0, v70
	v_add_f32_e32 v71, 1.0, v71
	v_mul_f32_e32 v88, v87, v87
	v_add_f32_e32 v81, 1.0, v64
	v_add_f32_e32 v86, 1.0, v65
	v_add_f32_e32 v87, 1.0, v66
	v_add_f32_e32 v89, 1.0, v67
	v_rcp_f32_e32 v64, v68
	v_rcp_f32_e32 v65, v69
	v_rcp_f32_e32 v66, v70
	v_rcp_f32_e32 v67, v71
	v_rcp_f32_e32 v68, v81
	v_rcp_f32_e32 v69, v86
	v_rcp_f32_e32 v70, v87
	v_rcp_f32_e32 v71, v89
	v_pk_mul_f32 v[64:65], v[88:89], v[64:65] op_sel_hi:[0,1]
	v_pk_mul_f32 v[66:67], v[88:89], v[66:67] op_sel_hi:[0,1]
	v_pk_mul_f32 v[68:69], v[88:89], v[68:69] op_sel_hi:[0,1]
	v_pk_mul_f32 v[70:71], v[88:89], v[70:71] op_sel_hi:[0,1]
	v_pk_mul_f32 v[66:67], v[78:79], v[66:67]
	v_pk_mul_f32 v[64:65], v[76:77], v[64:65]
	v_pk_mul_f32 v[70:71], v[74:75], v[70:71]
	v_pk_mul_f32 v[68:69], v[72:73], v[68:69]
	v_cvt_pk_bf16_f32 v64, v64, v65
	v_cvt_pk_bf16_f32 v65, v66, v67
	s_nop 0
	v_cvt_pk_bf16_f32 v66, v68, v69
	v_cvt_pk_bf16_f32 v67, v70, v71
	global_store_dwordx4 v[82:83], v[64:67], off sc1
	s_nop 1
	s_nop 0
	v_add_u32_e32 v64, 0x90, v132
	v_mad_i64_i32 v[66:67], s[26:27], v80, s46, v[120:121]
	v_lshl_add_u64 v[66:67], v[66:67], 0, v[122:123]
	s_waitcnt vmcnt(7)
	v_fmamk_f32 v65, v228, 0x3a000000, v152
	v_rsq_f32_e32 v71, v65
	v_ashrrev_i32_e32 v65, 31, v64
	v_lshl_add_u64 v[68:69], v[64:65], 2, s[8:9]
	v_mul_f32_e32 v70, 0xbfb8aa3b, v71
	v_pk_mul_f32 v[54:55], v[54:55], v[70:71] op_sel_hi:[1,0]
	v_pk_mul_f32 v[52:53], v[52:53], v[70:71] op_sel_hi:[1,0]
	v_pk_mul_f32 v[50:51], v[50:51], v[70:71] op_sel_hi:[1,0]
	v_pk_mul_f32 v[48:49], v[48:49], v[70:71] op_sel_hi:[1,0]
	v_exp_f32_e32 v52, v52
	v_exp_f32_e32 v53, v53
	v_exp_f32_e32 v54, v54
	v_exp_f32_e32 v55, v55
	v_exp_f32_e32 v48, v48
	v_exp_f32_e32 v49, v49
	v_exp_f32_e32 v50, v50
	v_exp_f32_e32 v51, v51
	v_add_f32_e32 v52, 1.0, v52
	v_add_f32_e32 v53, 1.0, v53
	v_add_f32_e32 v54, 1.0, v54
	v_add_f32_e32 v55, 1.0, v55
	v_mul_f32_e32 v72, v71, v71
	v_add_f32_e32 v65, 1.0, v48
	v_add_f32_e32 v70, 1.0, v49
	v_add_f32_e32 v71, 1.0, v50
	v_add_f32_e32 v73, 1.0, v51
	v_rcp_f32_e32 v48, v52
	v_rcp_f32_e32 v49, v53
	v_rcp_f32_e32 v50, v54
	v_rcp_f32_e32 v51, v55
	v_rcp_f32_e32 v52, v65
	v_rcp_f32_e32 v53, v70
	v_rcp_f32_e32 v54, v71
	v_rcp_f32_e32 v55, v73
	v_pk_mul_f32 v[48:49], v[72:73], v[48:49] op_sel_hi:[0,1]
	v_pk_mul_f32 v[50:51], v[72:73], v[50:51] op_sel_hi:[0,1]
	v_pk_mul_f32 v[52:53], v[72:73], v[52:53] op_sel_hi:[0,1]
	v_pk_mul_f32 v[54:55], v[72:73], v[54:55] op_sel_hi:[0,1]
	v_pk_mul_f32 v[50:51], v[62:63], v[50:51]
	v_pk_mul_f32 v[48:49], v[60:61], v[48:49]
	v_pk_mul_f32 v[54:55], v[58:59], v[54:55]
	v_pk_mul_f32 v[52:53], v[56:57], v[52:53]
	v_cvt_pk_bf16_f32 v48, v48, v49
	v_cvt_pk_bf16_f32 v49, v50, v51
	s_nop 0
	v_cvt_pk_bf16_f32 v50, v52, v53
	v_cvt_pk_bf16_f32 v51, v54, v55
	global_store_dwordx4 v[66:67], v[48:51], off sc1
	s_nop 1
	s_nop 0
	v_add_u32_e32 v48, 0xa0, v132
	v_mad_i64_i32 v[50:51], s[26:27], v64, s46, v[120:121]
	v_lshl_add_u64 v[50:51], v[50:51], 0, v[122:123]
	s_waitcnt vmcnt(7)
; __device__ __forceinline__ u32x4 pack8(f32x4 v0, f32x4 v1) { u32x4 w; w.x = cvt_pk_bf16(v0[0], v0[1]); w.y = cvt_pk_bf16(v0[2], v0[3]); w.z = cvt_pk_bf16(v1[0], v1[1]); w.w = cvt_pk_bf16(v1[2], v1[3]); return w; }
;     __device__ __forceinline__ void operator()(EPI_ARGS) const {
;         const int col0 = u.pn * 128 + wc * 32 + 8 * fq;
; #pragma unroll
;         for (int ai = 0; ai < 2; ++ai)
; #pragma unroll
;             for (int m = 0; m < 4; ++m) { const int row = EPI_ROW(ai, m); const float rs = __builtin_amdgcn_rsqf(rsq[row] * (1.f / DM) + RMS_EPS); f32x4 v0, v1;
;                 const float c1 = -1.4426950408889634f * rs, rs2 = rs * rs;
;                 { const f32x4 g = acc[ai][0][m][0], u = acc[ai][1][m][0]; f32x4 t = g * c1, r;
; #pragma unroll
;                   for (int e = 0; e < 4; ++e) t[e] = __builtin_amdgcn_exp2f(t[e]);
;                   t = t + 1.f;
; #pragma unroll
;                   for (int e = 0; e < 4; ++e) r[e] = __builtin_amdgcn_rcpf(t[e]);
;                   v0 = (g * u) * (r * rs2); }
;                 { const f32x4 g = acc[ai][0][m][1], u = acc[ai][1][m][1]; f32x4 t = g * c1, r;
; #pragma unroll
;                   for (int e = 0; e < 4; ++e) t[e] = __builtin_amdgcn_exp2f(t[e]);
;                   t = t + 1.f;
; #pragma unroll
;                   for (int e = 0; e < 4; ++e) r[e] = __builtin_amdgcn_rcpf(t[e]);
;                   v1 = (g * u) * (r * rs2); }
;                 *(u32x4*)(H + (size_t)row * DFF + col0) = pack8(v0, v1);
;                 if (m & 1) asm volatile("" ::: "memory"); }
	v_fmamk_f32 v49, v229, 0x3a000000, v152
	v_rsq_f32_e32 v55, v49
	v_ashrrev_i32_e32 v49, 31, v48
	v_lshl_add_u64 v[52:53], v[48:49], 2, s[8:9]
	v_mul_f32_e32 v54, 0xbfb8aa3b, v55
	v_pk_mul_f32 v[38:39], v[38:39], v[54:55] op_sel_hi:[1,0]
	v_pk_mul_f32 v[36:37], v[36:37], v[54:55] op_sel_hi:[1,0]
	v_pk_mul_f32 v[34:35], v[34:35], v[54:55] op_sel_hi:[1,0]
	v_pk_mul_f32 v[32:33], v[32:33], v[54:55] op_sel_hi:[1,0]
	v_exp_f32_e32 v36, v36
	v_exp_f32_e32 v37, v37
	v_exp_f32_e32 v38, v38
	v_exp_f32_e32 v39, v39
	v_exp_f32_e32 v32, v32
	v_exp_f32_e32 v33, v33
	v_exp_f32_e32 v34, v34
	v_exp_f32_e32 v35, v35
	v_add_f32_e32 v36, 1.0, v36
	v_add_f32_e32 v37, 1.0, v37
	v_add_f32_e32 v38, 1.0, v38
	v_add_f32_e32 v39, 1.0, v39
	v_mul_f32_e32 v56, v55, v55
	v_add_f32_e32 v49, 1.0, v32
	v_add_f32_e32 v54, 1.0, v33
	v_add_f32_e32 v55, 1.0, v34
	v_add_f32_e32 v57, 1.0, v35
	v_rcp_f32_e32 v32, v36
	v_rcp_f32_e32 v33, v37
	v_rcp_f32_e32 v34, v38
	v_rcp_f32_e32 v35, v39
	v_rcp_f32_e32 v36, v49
	v_rcp_f32_e32 v37, v54
	v_rcp_f32_e32 v38, v55
	v_rcp_f32_e32 v39, v57
	v_pk_mul_f32 v[32:33], v[56:57], v[32:33] op_sel_hi:[0,1]
	v_pk_mul_f32 v[34:35], v[56:57], v[34:35] op_sel_hi:[0,1]
	v_pk_mul_f32 v[36:37], v[56:57], v[36:37] op_sel_hi:[0,1]
	v_pk_mul_f32 v[38:39], v[56:57], v[38:39] op_sel_hi:[0,1]
	v_pk_mul_f32 v[34:35], v[46:47], v[34:35]
	v_pk_mul_f32 v[32:33], v[44:45], v[32:33]
	v_pk_mul_f32 v[38:39], v[42:43], v[38:39]
	v_pk_mul_f32 v[36:37], v[40:41], v[36:37]
	v_cvt_pk_bf16_f32 v32, v32, v33
	v_cvt_pk_bf16_f32 v33, v34, v35
	s_nop 0
	v_cvt_pk_bf16_f32 v34, v36, v37
	v_cvt_pk_bf16_f32 v35, v38, v39
	global_store_dwordx4 v[50:51], v[32:35], off sc1
	s_nop 1
	s_nop 0
	v_add_u32_e32 v32, 0xb0, v132
	v_mad_i64_i32 v[34:35], s[26:27], v48, s46, v[120:121]
	v_lshl_add_u64 v[34:35], v[34:35], 0, v[122:123]
	s_waitcnt vmcnt(7)
	v_fmamk_f32 v33, v230, 0x3a000000, v152
	v_rsq_f32_e32 v39, v33
	v_ashrrev_i32_e32 v33, 31, v32
	v_lshl_add_u64 v[36:37], v[32:33], 2, s[8:9]
	v_mul_f32_e32 v38, 0xbfb8aa3b, v39
	v_pk_mul_f32 v[22:23], v[22:23], v[38:39] op_sel_hi:[1,0]
	v_pk_mul_f32 v[20:21], v[20:21], v[38:39] op_sel_hi:[1,0]
	v_pk_mul_f32 v[18:19], v[18:19], v[38:39] op_sel_hi:[1,0]
	v_pk_mul_f32 v[16:17], v[16:17], v[38:39] op_sel_hi:[1,0]
	v_exp_f32_e32 v20, v20
	v_exp_f32_e32 v21, v21
	v_exp_f32_e32 v22, v22
	v_exp_f32_e32 v23, v23
	v_exp_f32_e32 v16, v16
	v_exp_f32_e32 v17, v17
	v_exp_f32_e32 v18, v18
	v_exp_f32_e32 v19, v19
	v_add_f32_e32 v20, 1.0, v20
	v_add_f32_e32 v21, 1.0, v21
	v_add_f32_e32 v22, 1.0, v22
	v_add_f32_e32 v23, 1.0, v23
	v_mul_f32_e32 v40, v39, v39
	v_add_f32_e32 v33, 1.0, v16
	v_add_f32_e32 v38, 1.0, v17
	v_add_f32_e32 v39, 1.0, v18
	v_add_f32_e32 v41, 1.0, v19
	v_rcp_f32_e32 v16, v20
	v_rcp_f32_e32 v17, v21
	v_rcp_f32_e32 v18, v22
	v_rcp_f32_e32 v19, v23
	v_rcp_f32_e32 v20, v33
	v_rcp_f32_e32 v21, v38
	v_rcp_f32_e32 v22, v39
	v_rcp_f32_e32 v23, v41
	v_pk_mul_f32 v[16:17], v[40:41], v[16:17] op_sel_hi:[0,1]
	v_pk_mul_f32 v[18:19], v[40:41], v[18:19] op_sel_hi:[0,1]
	v_pk_mul_f32 v[20:21], v[40:41], v[20:21] op_sel_hi:[0,1]
	v_pk_mul_f32 v[22:23], v[40:41], v[22:23] op_sel_hi:[0,1]
	v_pk_mul_f32 v[18:19], v[30:31], v[18:19]
	v_pk_mul_f32 v[16:17], v[28:29], v[16:17]
	v_pk_mul_f32 v[22:23], v[26:27], v[22:23]
	v_pk_mul_f32 v[20:21], v[24:25], v[20:21]
	v_cvt_pk_bf16_f32 v16, v16, v17
	v_cvt_pk_bf16_f32 v17, v18, v19
	s_nop 0
	v_cvt_pk_bf16_f32 v18, v20, v21
	v_cvt_pk_bf16_f32 v19, v22, v23
	global_store_dwordx4 v[34:35], v[16:19], off sc1
	s_nop 1
	s_waitcnt vmcnt(7)
	v_fmamk_f32 v16, v231, 0x3a000000, v152
	v_rsq_f32_e32 v19, v16
	v_mad_i64_i32 v[16:17], s[26:27], v32, s46, v[120:121]
	v_lshl_add_u64 v[16:17], v[16:17], 0, v[122:123]
	v_mul_f32_e32 v18, 0xbfb8aa3b, v19
	v_pk_mul_f32 v[10:11], v[10:11], v[18:19] op_sel_hi:[1,0]
	v_pk_mul_f32 v[8:9], v[8:9], v[18:19] op_sel_hi:[1,0]
	v_pk_mul_f32 v[6:7], v[6:7], v[18:19] op_sel_hi:[1,0]
	v_pk_mul_f32 v[4:5], v[4:5], v[18:19] op_sel_hi:[1,0]
	v_exp_f32_e32 v8, v8
	v_exp_f32_e32 v9, v9
	v_exp_f32_e32 v10, v10
	v_exp_f32_e32 v11, v11
	v_exp_f32_e32 v4, v4
	v_exp_f32_e32 v5, v5
	v_exp_f32_e32 v6, v6
	v_exp_f32_e32 v7, v7
	v_mul_f32_e32 v20, v19, v19
	v_add_f32_e32 v8, 1.0, v8
	v_add_f32_e32 v9, 1.0, v9
	v_add_f32_e32 v10, 1.0, v10
	v_add_f32_e32 v11, 1.0, v11
	v_add_f32_e32 v18, 1.0, v4
	v_add_f32_e32 v19, 1.0, v5
	v_add_f32_e32 v21, 1.0, v6
	v_add_f32_e32 v22, 1.0, v7
	v_rcp_f32_e32 v4, v8
	v_rcp_f32_e32 v5, v9
	v_rcp_f32_e32 v6, v10
	v_rcp_f32_e32 v7, v11
	v_rcp_f32_e32 v8, v18
	v_rcp_f32_e32 v9, v19
	v_rcp_f32_e32 v10, v21
	v_rcp_f32_e32 v11, v22
	v_pk_mul_f32 v[4:5], v[20:21], v[4:5] op_sel_hi:[0,1]
	v_pk_mul_f32 v[8:9], v[20:21], v[8:9] op_sel_hi:[0,1]
	v_pk_mul_f32 v[6:7], v[20:21], v[6:7] op_sel_hi:[0,1]
	v_pk_mul_f32 v[10:11], v[20:21], v[10:11] op_sel_hi:[0,1]
	v_pk_mul_f32 v[10:11], v[2:3], v[10:11]
	v_pk_mul_f32 v[2:3], v[0:1], v[8:9]
	v_pk_mul_f32 v[6:7], v[14:15], v[6:7]
	v_pk_mul_f32 v[4:5], v[12:13], v[4:5]
	s_nop 0
	v_cvt_pk_bf16_f32 v0, v4, v5
	v_cvt_pk_bf16_f32 v1, v6, v7
	v_cvt_pk_bf16_f32 v2, v2, v3
	v_cvt_pk_bf16_f32 v3, v10, v11
	global_store_dwordx4 v[16:17], v[0:3], off sc1
	s_cbranch_vccnz .LBB0_892
	s_andn2_b64 vcc, exec, s[6:7]
	s_cbranch_vccnz .LBB0_891
	s_barrier
	s_branch .LBB0_891

; __device__ __forceinline__ u32x4 pack8(f32x4 v0, f32x4 v1) { u32x4 w; w.x = cvt_pk_bf16(v0[0], v0[1]); w.y = cvt_pk_bf16(v0[2], v0[3]); w.z = cvt_pk_bf16(v1[0], v1[1]); w.w = cvt_pk_bf16(v1[2], v1[3]); return w; }
;     __device__ __forceinline__ void operator()(EPI_ARGS) const {
; #pragma unroll
;         for (int ai = 0; ai < 2; ++ai)
; #pragma unroll
;             for (int m = 0; m < 4; ++m) { const int row = EPI_ROW(ai, m); const float rstd = rsq ? __builtin_amdgcn_rsqf(rsq[row] * inv_n + RMS_EPS) : 1.f;
; #pragma unroll
;                 for (int bj = 0; bj < 2; ++bj) *(u32x4*)(O + (size_t)row * ld + EPI_COL(bj)) = pack8(acc[ai][bj][m][0] * rstd, acc[ai][bj][m][1] * rstd);
;                 asm volatile("" ::: "memory"); }
;     }
; __global__ void __launch_bounds__(512, 2) fwd_megakernel(Params p) {
;     ...
;         pg8::Gemm g{HMID, Wdown, DFF, DFF, DFF, 0, 0}; pg8::StaticOrder S; S.init(MROWS, DM, G, bid); EpiScaleRow E{(bf16_t*)p.out, 2 * DM, nullptr, 0.f};
;         for (int frep = 0; frep < FFN_REP; ++frep) pg8::gemm_phase<EpiScaleRow, pg8::StaticOrder>(ldsl, g, S, E);
.LBB0_968:
	v_lshl_add_u32 v132, s43, 8, v139
	v_lshl_or_b32 v152, s42, 8, v146
	v_ashrrev_i32_e32 v133, 31, v132
	v_cvt_pk_bf16_f32 v124, v124, v125
	v_cvt_pk_bf16_f32 v125, v126, v127
	v_cvt_pk_bf16_f32 v126, v120, v121
	v_lshlrev_b64 v[120:121], 13, v[132:133]
	v_ashrrev_i32_e32 v153, 31, v152
	v_cvt_pk_bf16_f32 v127, v122, v123
	v_lshl_add_u64 v[122:123], s[70:71], 0, v[120:121]
	v_lshlrev_b64 v[120:121], 1, v[152:153]
	v_lshl_add_u64 v[122:123], v[122:123], 0, v[120:121]
	global_store_dwordx4 v[122:123], v[124:127], off sc1
	v_cvt_pk_bf16_f32 v112, v112, v113
	v_cvt_pk_bf16_f32 v113, v114, v115
	v_cvt_pk_bf16_f32 v114, v104, v105
	v_cvt_pk_bf16_f32 v115, v106, v107
	global_store_dwordx4 v[122:123], v[112:115], off offset:256 sc1
	v_cvt_pk_bf16_f32 v104, v116, v117
	v_cvt_pk_bf16_f32 v105, v118, v119
	v_cvt_pk_bf16_f32 v106, v108, v109
	v_cvt_pk_bf16_f32 v107, v110, v111
	s_nop 1
	v_or_b32_e32 v112, 16, v132
	v_ashrrev_i32_e32 v113, 31, v112
	v_lshlrev_b64 v[108:109], 13, v[112:113]
	v_lshl_add_u64 v[108:109], s[70:71], 0, v[108:109]
	v_lshl_add_u64 v[108:109], v[108:109], 0, v[120:121]
	global_store_dwordx4 v[108:109], v[104:107], off sc1
	v_cvt_pk_bf16_f32 v96, v96, v97
	v_cvt_pk_bf16_f32 v97, v98, v99
	v_cvt_pk_bf16_f32 v98, v88, v89
	v_cvt_pk_bf16_f32 v99, v90, v91
	global_store_dwordx4 v[108:109], v[96:99], off offset:256 sc1
	v_cvt_pk_bf16_f32 v88, v100, v101
	v_cvt_pk_bf16_f32 v89, v102, v103
	v_cvt_pk_bf16_f32 v90, v92, v93
	v_cvt_pk_bf16_f32 v91, v94, v95
	s_nop 1
	v_or_b32_e32 v96, 32, v132
	v_ashrrev_i32_e32 v97, 31, v96
	v_lshlrev_b64 v[92:93], 13, v[96:97]
	v_lshl_add_u64 v[92:93], s[70:71], 0, v[92:93]
	v_lshl_add_u64 v[92:93], v[92:93], 0, v[120:121]
	global_store_dwordx4 v[92:93], v[88:91], off sc1
	v_cvt_pk_bf16_f32 v80, v80, v81
	v_cvt_pk_bf16_f32 v81, v82, v83
	v_cvt_pk_bf16_f32 v82, v72, v73
	v_cvt_pk_bf16_f32 v83, v74, v75
	global_store_dwordx4 v[92:93], v[80:83], off offset:256 sc1
	v_cvt_pk_bf16_f32 v72, v84, v85
	v_cvt_pk_bf16_f32 v73, v86, v87
	v_cvt_pk_bf16_f32 v74, v76, v77
	v_cvt_pk_bf16_f32 v75, v78, v79
	s_nop 1
	v_or_b32_e32 v80, 48, v132
	v_ashrrev_i32_e32 v81, 31, v80
	v_lshlrev_b64 v[76:77], 13, v[80:81]
	v_lshl_add_u64 v[76:77], s[70:71], 0, v[76:77]
	v_lshl_add_u64 v[76:77], v[76:77], 0, v[120:121]
	global_store_dwordx4 v[76:77], v[72:75], off sc1
	v_cvt_pk_bf16_f32 v68, v68, v69
	v_cvt_pk_bf16_f32 v69, v70, v71
	v_cvt_pk_bf16_f32 v70, v64, v65
	v_add_u32_e32 v64, 0x80, v132
	v_cvt_pk_bf16_f32 v71, v66, v67
	global_store_dwordx4 v[76:77], v[68:71], off offset:256 sc1
	v_ashrrev_i32_e32 v65, 31, v64
	v_cvt_pk_bf16_f32 v60, v60, v61
	v_cvt_pk_bf16_f32 v61, v62, v63
	v_cvt_pk_bf16_f32 v62, v56, v57
	v_lshlrev_b64 v[56:57], 13, v[64:65]
	v_lshl_add_u64 v[56:57], s[70:71], 0, v[56:57]
	v_lshl_add_u64 v[56:57], v[56:57], 0, v[120:121]
	v_cvt_pk_bf16_f32 v63, v58, v59
	global_store_dwordx4 v[56:57], v[60:63], off sc1
	v_cvt_pk_bf16_f32 v48, v48, v49
	v_cvt_pk_bf16_f32 v49, v50, v51
	v_cvt_pk_bf16_f32 v50, v40, v41
	v_cvt_pk_bf16_f32 v51, v42, v43
	global_store_dwordx4 v[56:57], v[48:51], off offset:256 sc1
	v_cvt_pk_bf16_f32 v40, v52, v53
	v_cvt_pk_bf16_f32 v41, v54, v55
	v_cvt_pk_bf16_f32 v42, v44, v45
	v_cvt_pk_bf16_f32 v43, v46, v47
	s_nop 1
	v_add_u32_e32 v48, 0x90, v132
	v_ashrrev_i32_e32 v49, 31, v48
	v_lshlrev_b64 v[44:45], 13, v[48:49]
	v_lshl_add_u64 v[44:45], s[70:71], 0, v[44:45]
	v_lshl_add_u64 v[44:45], v[44:45], 0, v[120:121]
	global_store_dwordx4 v[44:45], v[40:43], off sc1
	v_cvt_pk_bf16_f32 v32, v32, v33
	v_cvt_pk_bf16_f32 v33, v34, v35
	v_cvt_pk_bf16_f32 v34, v24, v25
	v_cvt_pk_bf16_f32 v35, v26, v27
	global_store_dwordx4 v[44:45], v[32:35], off offset:256 sc1
	v_cvt_pk_bf16_f32 v24, v36, v37
	v_cvt_pk_bf16_f32 v25, v38, v39
	v_cvt_pk_bf16_f32 v26, v28, v29
	v_cvt_pk_bf16_f32 v27, v30, v31
	s_nop 1
	v_add_u32_e32 v32, 0xa0, v132
	v_ashrrev_i32_e32 v33, 31, v32
	v_lshlrev_b64 v[28:29], 13, v[32:33]
	v_lshl_add_u64 v[28:29], s[70:71], 0, v[28:29]
	v_lshl_add_u64 v[28:29], v[28:29], 0, v[120:121]
	global_store_dwordx4 v[28:29], v[24:27], off sc1
	v_cvt_pk_bf16_f32 v16, v16, v17
	v_cvt_pk_bf16_f32 v17, v18, v19
	v_cvt_pk_bf16_f32 v18, v8, v9
	v_cvt_pk_bf16_f32 v19, v10, v11
	global_store_dwordx4 v[28:29], v[16:19], off offset:256 sc1
	v_cvt_pk_bf16_f32 v8, v20, v21
	v_cvt_pk_bf16_f32 v9, v22, v23
	v_cvt_pk_bf16_f32 v10, v12, v13
	v_cvt_pk_bf16_f32 v11, v14, v15
	s_nop 1
	v_add_u32_e32 v16, 0xb0, v132
	v_ashrrev_i32_e32 v17, 31, v16
	v_lshlrev_b64 v[12:13], 13, v[16:17]
	v_lshl_add_u64 v[12:13], s[70:71], 0, v[12:13]
	v_lshl_add_u64 v[12:13], v[12:13], 0, v[120:121]
	global_store_dwordx4 v[12:13], v[8:11], off sc1
	v_cvt_pk_bf16_f32 v4, v4, v5
	v_cvt_pk_bf16_f32 v5, v6, v7
	v_cvt_pk_bf16_f32 v6, v0, v1
	v_cvt_pk_bf16_f32 v7, v2, v3
	global_store_dwordx4 v[12:13], v[4:7], off offset:256 sc1
	s_andn2_b64 vcc, exec, s[4:5]
	s_mov_b64 s[4:5], -1
	s_cbranch_vccnz .LBB0_961
	s_andn2_b64 vcc, exec, s[6:7]
	s_cbranch_vccnz .LBB0_960
	s_barrier
	s_branch .LBB0_960
